# GEMM main loop back-edge rotation: pointer/counter updates and next-iteration selects moved before the loop-back barrier
# baseline (speedup 1.0000x reference)
; #define PG8_STAGE(bufoff, gbase, voff) do { _Pragma("unroll") for (int _i = 0; _i < 2; ++_i) \
;         __builtin_amdgcn_global_load_lds((const unsigned*)((const char*)(gbase) + (voff)[_i]), (LAS unsigned*)(lds + (bufoff) + ldsw + _i * 8192), 16, 0, 0); } while (0)
; #define PG8_LDA(dst, b, h) do { _Pragma("unroll") for (int m = 0; m < 4; ++m) _Pragma("unroll") for (int k = 0; k < 2; ++k) dst[m][k] = *(const LAS bf16x8*)(lds + PG8_SA(b, h) + aoff + m * 2048 + k * 1024); } while (0)
; #define PG8_LDB(dst, b, h) do { _Pragma("unroll") for (int n = 0; n < 2; ++n) _Pragma("unroll") for (int k = 0; k < 2; ++k) dst[n][k] = *(const LAS bf16x8*)(lds + PG8_SB(b, h) + boff + n * 2048 + k * 1024); } while (0)
; #define PG8_MMA(ai, bj, At, Bt) do { __builtin_amdgcn_s_setprio(1); _Pragma("unroll") for (int m = 0; m < 4; ++m) _Pragma("unroll") for (int n = 0; n < 2; ++n) _Pragma("unroll") for (int k = 0; k < 2; ++k) \
;         acc[ai][bj][m][n] = __builtin_amdgcn_mfma_f32_16x16x32_bf16(Bt[n][k], At[m][k], acc[ai][bj][m][n], 0, 0, 0); __builtin_amdgcn_s_setprio(0); } while (0)
; #define PG8_WAIT_V(n) asm volatile("s_waitcnt vmcnt(" #n ")" ::: "memory")
; #define PG8_WAIT_L(n) asm volatile("s_waitcnt lgkmcnt(" #n ")" ::: "memory")
; #define PG8_BAR __builtin_amdgcn_s_barrier()
; #define PG8_SCHED __builtin_amdgcn_sched_barrier(0)
; __device__ __forceinline__ void gemm_phase(LAS unsigned char* lds, const GemmD g, const Sched& S, const Epi& E) {
;     ...
;         for (int t = 0; t < nt; t += 2) {
;             const bool last = (t == nt - 2);
;             const char* a1 = cA + (size_t)(t + 1) * kstep;
;             const char* a2 = last ? nA : cA + (size_t)(t + 2) * kstep; const char* b2 = last ? nB : cB + (size_t)(t + 2) * kstep;
;             const char* a3 = a2 + kstep; const char* b3 = b2 + kstep;
;             PG8_LDB(B0, 0, 0); PG8_LDB(B1, 0, 1); PG8_SCHED; PG8_LDA(At, 0, 0); PG8_STAGE(PG8_SA(1, 1), a1 + hstepA, voffA);
;             PG8_WAIT_V(8); PG8_WAIT_L(0); PG8_BAR; PG8_MMA(0, 0, At, B0); PG8_MMA(0, 1, At, B1); PG8_BAR; PG8_SCHED;
;             PG8_LDA(At, 0, 1); PG8_STAGE(PG8_SB(0, 0), b2, voffB); PG8_STAGE(PG8_SB(0, 1), b2 + hstepB, voffB); PG8_STAGE(PG8_SA(0, 0), a2, voffA);
;             PG8_WAIT_V(8); PG8_WAIT_L(0); PG8_BAR; PG8_MMA(1, 0, At, B0); PG8_MMA(1, 1, At, B1); PG8_BAR; PG8_SCHED;
.Lprio_done:
.LBB0_215:
	s_add_i32 s92, s26, 2
	s_add_u32 s93, s8, 0x80
	s_addc_u32 s27, s9, 0
	s_add_i32 s22, 0, 0x10000
	s_cmp_eq_u32 s11, s26
	s_cselect_b32 s27, s1, s27
	s_cselect_b32 s26, s0, s93
	s_cselect_b32 vcc_hi, s17, s35
	s_cselect_b32 vcc_lo, s16, s34
	s_add_i32 s23, 0, 0x14000
.Lgemm_head:
	v_add_u32_e32 v0, s22, v160
	ds_read_b128 v[130:133], v0
	ds_read_b128 v[146:149], v0 offset:1024
	ds_read_b128 v[150:153], v0 offset:2048
	ds_read_b128 v[154:157], v0 offset:3072
	v_add_u32_e32 v0, s23, v160
	ds_read_b128 v[162:165], v0
	ds_read_b128 v[166:169], v0 offset:1024
	ds_read_b128 v[170:173], v0 offset:2048
	ds_read_b128 v[174:177], v0 offset:3072
	s_add_i32 m0, s31, 0xc000
	ds_read_b128 v[182:185], v161
	ds_read_b128 v[186:189], v161 offset:1024
	ds_read_b128 v[190:193], v161 offset:2048
	ds_read_b128 v[216:219], v161 offset:3072
	ds_read_b128 v[220:223], v161 offset:4096
	ds_read_b128 v[224:227], v161 offset:5120
	ds_read_b128 v[228:231], v161 offset:6144
	ds_read_b128 v[236:239], v161 offset:7168
	global_load_lds_dwordx4 v142, s[8:9]
	s_add_i32 m0, s31, 0xe000
	s_nop 0
	global_load_lds_dwordx4 v144, s[8:9]
	s_waitcnt vmcnt(8)
	s_waitcnt lgkmcnt(0)
	s_barrier
	s_waitcnt lgkmcnt(0)
	v_mfma_f32_16x16x32_bf16 v[126:129], v[130:133], v[182:185], v[126:129]
	v_mfma_f32_16x16x32_bf16 v[122:125], v[150:153], v[182:185], v[122:125]
	v_mfma_f32_16x16x32_bf16 v[110:113], v[130:133], v[190:193], v[110:113]
	v_mfma_f32_16x16x32_bf16 v[106:109], v[150:153], v[190:193], v[106:109]
	v_mfma_f32_16x16x32_bf16 v[94:97], v[130:133], v[220:223], v[94:97]
	v_mfma_f32_16x16x32_bf16 v[90:93], v[150:153], v[220:223], v[90:93]
	v_mfma_f32_16x16x32_bf16 v[78:81], v[130:133], v[228:231], v[78:81]
	v_mfma_f32_16x16x32_bf16 v[74:77], v[150:153], v[228:231], v[74:77]
	v_mfma_f32_16x16x32_bf16 v[126:129], v[146:149], v[186:189], v[126:129]
	v_mfma_f32_16x16x32_bf16 v[122:125], v[154:157], v[186:189], v[122:125]
	v_mfma_f32_16x16x32_bf16 v[110:113], v[146:149], v[216:219], v[110:113]
	v_mfma_f32_16x16x32_bf16 v[106:109], v[154:157], v[216:219], v[106:109]
	v_mfma_f32_16x16x32_bf16 v[94:97], v[146:149], v[224:227], v[94:97]
	v_mfma_f32_16x16x32_bf16 v[90:93], v[154:157], v[224:227], v[90:93]
	v_mfma_f32_16x16x32_bf16 v[78:81], v[146:149], v[236:239], v[78:81]
	v_mfma_f32_16x16x32_bf16 v[74:77], v[154:157], v[236:239], v[74:77]
	v_mfma_f32_16x16x32_bf16 v[118:121], v[162:165], v[182:185], v[118:121]
	v_mfma_f32_16x16x32_bf16 v[114:117], v[170:173], v[182:185], v[114:117]
	v_mfma_f32_16x16x32_bf16 v[102:105], v[162:165], v[190:193], v[102:105]
	v_mfma_f32_16x16x32_bf16 v[98:101], v[170:173], v[190:193], v[98:101]
	v_mfma_f32_16x16x32_bf16 v[86:89], v[162:165], v[220:223], v[86:89]
	v_mfma_f32_16x16x32_bf16 v[82:85], v[170:173], v[220:223], v[82:85]
	v_mfma_f32_16x16x32_bf16 v[70:73], v[162:165], v[228:231], v[70:73]
	v_mfma_f32_16x16x32_bf16 v[66:69], v[170:173], v[228:231], v[66:69]
	v_mfma_f32_16x16x32_bf16 v[118:121], v[166:169], v[186:189], v[118:121]
	v_mfma_f32_16x16x32_bf16 v[114:117], v[174:177], v[186:189], v[114:117]
	v_mfma_f32_16x16x32_bf16 v[102:105], v[166:169], v[216:219], v[102:105]
	v_mfma_f32_16x16x32_bf16 v[98:101], v[174:177], v[216:219], v[98:101]
	v_mfma_f32_16x16x32_bf16 v[86:89], v[166:169], v[224:227], v[86:89]
	v_mfma_f32_16x16x32_bf16 v[82:85], v[174:177], v[224:227], v[82:85]
	v_mfma_f32_16x16x32_bf16 v[70:73], v[166:169], v[236:239], v[70:73]
	v_mfma_f32_16x16x32_bf16 v[66:69], v[174:177], v[236:239], v[66:69]
	s_barrier
	s_add_i32 s22, s22, s30
	s_mov_b32 m0, s22
	ds_read_b128 v[182:185], v161 offset:16384
	ds_read_b128 v[186:189], v161 offset:17408
	ds_read_b128 v[190:193], v161 offset:18432
	ds_read_b128 v[216:219], v161 offset:19456
	ds_read_b128 v[220:223], v161 offset:20480
	ds_read_b128 v[224:227], v161 offset:21504
	ds_read_b128 v[228:231], v161 offset:22528
	ds_read_b128 v[236:239], v161 offset:23552
	global_load_lds_dwordx4 v136, vcc
	s_add_i32 m0, s22, 0x2000
	s_add_i32 s22, s23, s30
	global_load_lds_dwordx4 v140, vcc
	s_mov_b32 m0, s22
	s_nop 0
	global_load_lds_dwordx4 v253, vcc
	s_add_i32 m0, s22, 0x2000
	s_nop 0
	global_load_lds_dwordx4 v254, vcc
	s_mov_b32 m0, s31
	s_nop 0
	global_load_lds_dwordx4 v134, s[26:27]
	s_mov_b32 m0, s14
	s_nop 0
	global_load_lds_dwordx4 v138, s[26:27]
	s_waitcnt vmcnt(8)
	s_waitcnt lgkmcnt(0)
	s_barrier
	s_waitcnt lgkmcnt(0)
	v_mfma_f32_16x16x32_bf16 v[62:65], v[130:133], v[182:185], v[62:65]
	v_mfma_f32_16x16x32_bf16 v[58:61], v[150:153], v[182:185], v[58:61]
	v_mfma_f32_16x16x32_bf16 v[46:49], v[130:133], v[190:193], v[46:49]
	v_mfma_f32_16x16x32_bf16 v[42:45], v[150:153], v[190:193], v[42:45]
	v_mfma_f32_16x16x32_bf16 v[30:33], v[130:133], v[220:223], v[30:33]
	v_mfma_f32_16x16x32_bf16 v[26:29], v[150:153], v[220:223], v[26:29]
	v_mfma_f32_16x16x32_bf16 v[14:17], v[130:133], v[228:231], v[14:17]
	v_mfma_f32_16x16x32_bf16 v[10:13], v[150:153], v[228:231], v[10:13]
	v_mfma_f32_16x16x32_bf16 v[62:65], v[146:149], v[186:189], v[62:65]
	v_mfma_f32_16x16x32_bf16 v[58:61], v[154:157], v[186:189], v[58:61]
	v_mfma_f32_16x16x32_bf16 v[46:49], v[146:149], v[216:219], v[46:49]
	v_mfma_f32_16x16x32_bf16 v[42:45], v[154:157], v[216:219], v[42:45]
	v_mfma_f32_16x16x32_bf16 v[30:33], v[146:149], v[224:227], v[30:33]
	v_mfma_f32_16x16x32_bf16 v[26:29], v[154:157], v[224:227], v[26:29]
	v_mfma_f32_16x16x32_bf16 v[14:17], v[146:149], v[236:239], v[14:17]
	v_mfma_f32_16x16x32_bf16 v[10:13], v[154:157], v[236:239], v[10:13]
	v_mfma_f32_16x16x32_bf16 v[54:57], v[162:165], v[182:185], v[54:57]
	v_mfma_f32_16x16x32_bf16 v[50:53], v[170:173], v[182:185], v[50:53]
	v_mfma_f32_16x16x32_bf16 v[38:41], v[162:165], v[190:193], v[38:41]
	v_mfma_f32_16x16x32_bf16 v[34:37], v[170:173], v[190:193], v[34:37]
	v_mfma_f32_16x16x32_bf16 v[22:25], v[162:165], v[220:223], v[22:25]
	v_mfma_f32_16x16x32_bf16 v[18:21], v[170:173], v[220:223], v[18:21]
	v_mfma_f32_16x16x32_bf16 v[6:9], v[162:165], v[228:231], v[6:9]
	v_mfma_f32_16x16x32_bf16 v[2:5], v[170:173], v[228:231], v[2:5]
	v_mfma_f32_16x16x32_bf16 v[54:57], v[166:169], v[186:189], v[54:57]
	v_mfma_f32_16x16x32_bf16 v[50:53], v[174:177], v[186:189], v[50:53]
	v_mfma_f32_16x16x32_bf16 v[38:41], v[166:169], v[216:219], v[38:41]
	v_mfma_f32_16x16x32_bf16 v[34:37], v[174:177], v[216:219], v[34:37]
	v_mfma_f32_16x16x32_bf16 v[22:25], v[166:169], v[224:227], v[22:25]
	v_mfma_f32_16x16x32_bf16 v[18:21], v[174:177], v[224:227], v[18:21]
	v_mfma_f32_16x16x32_bf16 v[6:9], v[166:169], v[236:239], v[6:9]
	v_mfma_f32_16x16x32_bf16 v[2:5], v[174:177], v[236:239], v[2:5]
	s_barrier
; #define PG8_STAGE(bufoff, gbase, voff) do { _Pragma("unroll") for (int _i = 0; _i < 2; ++_i) \
;         __builtin_amdgcn_global_load_lds((const unsigned*)((const char*)(gbase) + (voff)[_i]), (LAS unsigned*)(lds + (bufoff) + ldsw + _i * 8192), 16, 0, 0); } while (0)
; #define PG8_LDA(dst, b, h) do { _Pragma("unroll") for (int m = 0; m < 4; ++m) _Pragma("unroll") for (int k = 0; k < 2; ++k) dst[m][k] = *(const LAS bf16x8*)(lds + PG8_SA(b, h) + aoff + m * 2048 + k * 1024); } while (0)
; #define PG8_LDB(dst, b, h) do { _Pragma("unroll") for (int n = 0; n < 2; ++n) _Pragma("unroll") for (int k = 0; k < 2; ++k) dst[n][k] = *(const LAS bf16x8*)(lds + PG8_SB(b, h) + boff + n * 2048 + k * 1024); } while (0)
; #define PG8_MMA(ai, bj, At, Bt) do { __builtin_amdgcn_s_setprio(1); _Pragma("unroll") for (int m = 0; m < 4; ++m) _Pragma("unroll") for (int n = 0; n < 2; ++n) _Pragma("unroll") for (int k = 0; k < 2; ++k) \
;         acc[ai][bj][m][n] = __builtin_amdgcn_mfma_f32_16x16x32_bf16(Bt[n][k], At[m][k], acc[ai][bj][m][n], 0, 0, 0); __builtin_amdgcn_s_setprio(0); } while (0)
; #define PG8_WAIT_V(n) asm volatile("s_waitcnt vmcnt(" #n ")" ::: "memory")
; #define PG8_WAIT_L(n) asm volatile("s_waitcnt lgkmcnt(" #n ")" ::: "memory")
; #define PG8_BAR __builtin_amdgcn_s_barrier()
; #define PG8_SCHED __builtin_amdgcn_sched_barrier(0)
; __device__ __forceinline__ void gemm_phase(LAS unsigned char* lds, const GemmD g, const Sched& S, const Epi& E) {
;     ...
;             const bool last = (t == nt - 2);
;             const char* a1 = cA + (size_t)(t + 1) * kstep;
;             const char* a2 = last ? nA : cA + (size_t)(t + 2) * kstep; const char* b2 = last ? nB : cB + (size_t)(t + 2) * kstep;
;             const char* a3 = a2 + kstep; const char* b3 = b2 + kstep;
;     ...
;             PG8_LDB(B0, 1, 0); PG8_LDB(B1, 1, 1); PG8_SCHED; PG8_LDA(At, 1, 0); PG8_STAGE(PG8_SA(0, 1), a2 + hstepA, voffA);
;             PG8_WAIT_V(8); PG8_WAIT_L(0); PG8_BAR; PG8_MMA(0, 0, At, B0); PG8_MMA(0, 1, At, B1); PG8_BAR; PG8_SCHED;
;             PG8_LDA(At, 1, 1); PG8_STAGE(PG8_SB(1, 0), b3, voffB); PG8_STAGE(PG8_SB(1, 1), b3 + hstepB, voffB); PG8_STAGE(PG8_SA(1, 0), a3, voffA);
;             PG8_WAIT_V(8); PG8_WAIT_L(0); PG8_BAR; PG8_MMA(1, 0, At, B0); PG8_MMA(1, 1, At, B1); PG8_BAR; PG8_SCHED;
;         }
	s_add_i32 s22, 0, 0x18000
	v_add_u32_e32 v0, s22, v160
	s_add_i32 s23, 0, 0x1c000
	ds_read_b128 v[130:133], v0
	ds_read_b128 v[146:149], v0 offset:1024
	ds_read_b128 v[150:153], v0 offset:2048
	ds_read_b128 v[154:157], v0 offset:3072
	v_add_u32_e32 v0, s23, v160
	ds_read_b128 v[162:165], v0
	ds_read_b128 v[166:169], v0 offset:1024
	ds_read_b128 v[170:173], v0 offset:2048
	ds_read_b128 v[174:177], v0 offset:3072
	s_mov_b32 m0, s15
	ds_read_b128 v[182:185], v161 offset:32768
	ds_read_b128 v[186:189], v161 offset:33792
	ds_read_b128 v[190:193], v161 offset:34816
	ds_read_b128 v[216:219], v161 offset:35840
	ds_read_b128 v[220:223], v161 offset:36864
	ds_read_b128 v[224:227], v161 offset:37888
	ds_read_b128 v[228:231], v161 offset:38912
	ds_read_b128 v[236:239], v161 offset:39936
	global_load_lds_dwordx4 v142, s[26:27]
	s_mov_b32 m0, s10
	s_nop 0
	global_load_lds_dwordx4 v144, s[26:27]
	s_waitcnt vmcnt(8)
	s_waitcnt lgkmcnt(0)
	s_barrier
	s_waitcnt lgkmcnt(0)
	v_mfma_f32_16x16x32_bf16 v[126:129], v[130:133], v[182:185], v[126:129]
	v_mfma_f32_16x16x32_bf16 v[122:125], v[150:153], v[182:185], v[122:125]
	v_mfma_f32_16x16x32_bf16 v[110:113], v[130:133], v[190:193], v[110:113]
	v_mfma_f32_16x16x32_bf16 v[106:109], v[150:153], v[190:193], v[106:109]
	v_mfma_f32_16x16x32_bf16 v[94:97], v[130:133], v[220:223], v[94:97]
	v_mfma_f32_16x16x32_bf16 v[90:93], v[150:153], v[220:223], v[90:93]
	v_mfma_f32_16x16x32_bf16 v[78:81], v[130:133], v[228:231], v[78:81]
	v_mfma_f32_16x16x32_bf16 v[74:77], v[150:153], v[228:231], v[74:77]
	v_mfma_f32_16x16x32_bf16 v[126:129], v[146:149], v[186:189], v[126:129]
	v_mfma_f32_16x16x32_bf16 v[122:125], v[154:157], v[186:189], v[122:125]
	v_mfma_f32_16x16x32_bf16 v[110:113], v[146:149], v[216:219], v[110:113]
	v_mfma_f32_16x16x32_bf16 v[106:109], v[154:157], v[216:219], v[106:109]
	v_mfma_f32_16x16x32_bf16 v[94:97], v[146:149], v[224:227], v[94:97]
	v_mfma_f32_16x16x32_bf16 v[90:93], v[154:157], v[224:227], v[90:93]
	v_mfma_f32_16x16x32_bf16 v[78:81], v[146:149], v[236:239], v[78:81]
	v_mfma_f32_16x16x32_bf16 v[74:77], v[154:157], v[236:239], v[74:77]
	v_mfma_f32_16x16x32_bf16 v[118:121], v[162:165], v[182:185], v[118:121]
	v_mfma_f32_16x16x32_bf16 v[114:117], v[170:173], v[182:185], v[114:117]
	v_mfma_f32_16x16x32_bf16 v[102:105], v[162:165], v[190:193], v[102:105]
	v_mfma_f32_16x16x32_bf16 v[98:101], v[170:173], v[190:193], v[98:101]
	v_mfma_f32_16x16x32_bf16 v[86:89], v[162:165], v[220:223], v[86:89]
	v_mfma_f32_16x16x32_bf16 v[82:85], v[170:173], v[220:223], v[82:85]
	v_mfma_f32_16x16x32_bf16 v[70:73], v[162:165], v[228:231], v[70:73]
	v_mfma_f32_16x16x32_bf16 v[66:69], v[170:173], v[228:231], v[66:69]
	v_mfma_f32_16x16x32_bf16 v[118:121], v[166:169], v[186:189], v[118:121]
	v_mfma_f32_16x16x32_bf16 v[114:117], v[174:177], v[186:189], v[114:117]
	v_mfma_f32_16x16x32_bf16 v[102:105], v[166:169], v[216:219], v[102:105]
	v_mfma_f32_16x16x32_bf16 v[98:101], v[174:177], v[216:219], v[98:101]
	v_mfma_f32_16x16x32_bf16 v[86:89], v[166:169], v[224:227], v[86:89]
	v_mfma_f32_16x16x32_bf16 v[82:85], v[174:177], v[224:227], v[82:85]
	v_mfma_f32_16x16x32_bf16 v[70:73], v[166:169], v[236:239], v[70:73]
	v_mfma_f32_16x16x32_bf16 v[66:69], v[174:177], v[236:239], v[66:69]
	s_barrier
	s_add_i32 s22, s22, s30
	s_add_u32 vcc_lo, vcc_lo, s84
	s_addc_u32 vcc_hi, vcc_hi, s85
	s_add_u32 s26, s26, s84
	s_addc_u32 s27, s27, s85
	s_mov_b32 m0, s22
	ds_read_b128 v[182:185], v161 offset:49152
	ds_read_b128 v[186:189], v161 offset:50176
	ds_read_b128 v[190:193], v161 offset:51200
	ds_read_b128 v[216:219], v161 offset:52224
	ds_read_b128 v[220:223], v161 offset:53248
	ds_read_b128 v[224:227], v161 offset:54272
	ds_read_b128 v[228:231], v161 offset:55296
	ds_read_b128 v[236:239], v161 offset:56320
	global_load_lds_dwordx4 v136, vcc
	s_add_i32 m0, s22, 0x2000
	s_add_i32 s22, s23, s30
	global_load_lds_dwordx4 v140, vcc
	s_mov_b32 m0, s22
	s_nop 0
	global_load_lds_dwordx4 v253, vcc
	s_add_i32 m0, s22, 0x2000
	s_nop 0
	global_load_lds_dwordx4 v254, vcc
	s_mov_b32 m0, s18
	s_nop 0
	global_load_lds_dwordx4 v134, s[26:27]
	s_mov_b32 m0, s19
	s_nop 0
	global_load_lds_dwordx4 v138, s[26:27]
	s_waitcnt vmcnt(8)
	s_waitcnt lgkmcnt(0)
	s_barrier
	s_waitcnt lgkmcnt(0)
	v_mfma_f32_16x16x32_bf16 v[62:65], v[130:133], v[182:185], v[62:65]
	v_mfma_f32_16x16x32_bf16 v[58:61], v[150:153], v[182:185], v[58:61]
	v_mfma_f32_16x16x32_bf16 v[46:49], v[130:133], v[190:193], v[46:49]
	v_mfma_f32_16x16x32_bf16 v[42:45], v[150:153], v[190:193], v[42:45]
	v_mfma_f32_16x16x32_bf16 v[30:33], v[130:133], v[220:223], v[30:33]
	v_mfma_f32_16x16x32_bf16 v[26:29], v[150:153], v[220:223], v[26:29]
	v_mfma_f32_16x16x32_bf16 v[14:17], v[130:133], v[228:231], v[14:17]
	v_mfma_f32_16x16x32_bf16 v[10:13], v[150:153], v[228:231], v[10:13]
	v_mfma_f32_16x16x32_bf16 v[62:65], v[146:149], v[186:189], v[62:65]
	v_mfma_f32_16x16x32_bf16 v[58:61], v[154:157], v[186:189], v[58:61]
	v_mfma_f32_16x16x32_bf16 v[46:49], v[146:149], v[216:219], v[46:49]
	v_mfma_f32_16x16x32_bf16 v[42:45], v[154:157], v[216:219], v[42:45]
	v_mfma_f32_16x16x32_bf16 v[30:33], v[146:149], v[224:227], v[30:33]
	v_mfma_f32_16x16x32_bf16 v[26:29], v[154:157], v[224:227], v[26:29]
	v_mfma_f32_16x16x32_bf16 v[14:17], v[146:149], v[236:239], v[14:17]
	v_mfma_f32_16x16x32_bf16 v[10:13], v[154:157], v[236:239], v[10:13]
	v_mfma_f32_16x16x32_bf16 v[54:57], v[162:165], v[182:185], v[54:57]
	v_mfma_f32_16x16x32_bf16 v[50:53], v[170:173], v[182:185], v[50:53]
	v_mfma_f32_16x16x32_bf16 v[38:41], v[162:165], v[190:193], v[38:41]
	v_mfma_f32_16x16x32_bf16 v[34:37], v[170:173], v[190:193], v[34:37]
	v_mfma_f32_16x16x32_bf16 v[22:25], v[162:165], v[220:223], v[22:25]
	v_mfma_f32_16x16x32_bf16 v[18:21], v[170:173], v[220:223], v[18:21]
	v_mfma_f32_16x16x32_bf16 v[6:9], v[162:165], v[228:231], v[6:9]
	v_mfma_f32_16x16x32_bf16 v[2:5], v[170:173], v[228:231], v[2:5]
	v_mfma_f32_16x16x32_bf16 v[54:57], v[166:169], v[186:189], v[54:57]
	v_mfma_f32_16x16x32_bf16 v[50:53], v[174:177], v[186:189], v[50:53]
	v_mfma_f32_16x16x32_bf16 v[38:41], v[166:169], v[216:219], v[38:41]
	v_mfma_f32_16x16x32_bf16 v[34:37], v[174:177], v[216:219], v[34:37]
	v_mfma_f32_16x16x32_bf16 v[22:25], v[166:169], v[224:227], v[22:25]
	v_mfma_f32_16x16x32_bf16 v[18:21], v[174:177], v[224:227], v[18:21]
	v_mfma_f32_16x16x32_bf16 v[6:9], v[166:169], v[236:239], v[6:9]
	v_mfma_f32_16x16x32_bf16 v[2:5], v[174:177], v[236:239], v[2:5]
	s_add_u32 s8, s8, 0x100
	s_addc_u32 s9, s9, 0
	s_add_u32 s34, s34, 0x100
	s_addc_u32 s35, s35, 0
	s_mov_b32 s26, s92
	s_cmp_ge_u32 s92, s12
	s_cbranch_scc1 .Lgemm_exit
	s_add_i32 s92, s26, 2
	s_add_u32 s93, s8, 0x80
	s_addc_u32 s27, s9, 0
	s_add_i32 s22, 0, 0x10000
	s_cmp_eq_u32 s11, s26
	s_cselect_b32 s27, s1, s27
	s_cselect_b32 s26, s0, s93
	s_cselect_b32 vcc_hi, s17, s35
	s_cselect_b32 vcc_lo, s16, s34
	s_add_i32 s23, 0, 0x14000
	s_barrier
	s_branch .Lgemm_head
; #define PG8_BAR __builtin_amdgcn_s_barrier()
; __device__ __forceinline__ void gemm_phase(LAS unsigned char* lds, const GemmD g, const Sched& S, const Epi& E) {
;     ...
;         }
;         if (wr == 0) PG8_BAR;
;         epi_run(E, acc, cur, wr, wc, fr, fq);
.Lgemm_exit:
	s_barrier
	s_setprio 0
	v_readlane_b32 s8, v250, 24
	v_readlane_b32 s9, v250, 25
	s_and_b64 vcc, exec, s[8:9]
	s_cbranch_vccz .LBB0_219
	s_barrier
	s_cmp_lt_i32 s96, 4
	s_mov_b64 s[8:9], -1
	s_cbranch_scc0 .LBB0_220
